# residual epilogue: 7 of the second half's 8 XB loads issued with the first half's loads (one exposed round trip instead of two); per-row vmcnt ladder replaced by s_nop 1 (store-data WAR wait states)
# baseline (speedup 1.0000x reference)
;     __device__ __forceinline__ void operator()(AccRef acc, const pg8::Unit& u, int wr, int wc, int fr, int fq) const {
;         const int row0 = u.pm * 256 + wr * 64 + fr, col0 = u.pn * 256 + wc * 32 + 8 * fq;
; #pragma unroll
;         for (int ai = 0; ai < 2; ++ai) {
;             v4u xw[4][2];
; #pragma unroll
;             for (int m = 0; m < 4; ++m)
; #pragma unroll
;                 for (int bj = 0; bj < 2; ++bj) xw[m][bj] = *(const v4u*)(xb + (size_t)(row0 + ai * 128 + m * 16) * D + col0 + bj * 128);
; #pragma unroll
;             for (int m = 0; m < 4; ++m) {
;                 const int row = row0 + ai * 128 + m * 16;
;                 float ss = 0.f;
; #pragma unroll
;                 for (int bj = 0; bj < 2; ++bj) {
;                     const size_t p = (size_t)row * D + col0 + bj * 128;
;                     const v4u w0 = xw[m][bj];
;                     f32x4 a = {bflo(w0.x), bfhi(w0.x), bflo(w0.y), bfhi(w0.y)}, b = {bflo(w0.z), bfhi(w0.z), bflo(w0.w), bfhi(w0.w)};
;                     a = a + acc[ai][bj][m][0] * scale; b = b + acc[ai][bj][m][1] * scale;
;                     if (outf) { *(f32x4*)(outf + p) = a; *(f32x4*)(outf + p + 4) = b; }
.LBB0_378:
	s_lshl_b32 s3, s45, 8
	s_add_i32 s3, s3, s71
	v_add_u32_e32 v42, s3, v245
	s_lshl_b32 s3, s40, 8
	s_or_b32 s3, s3, s67
	v_lshl_add_u32 v40, v244, 3, s3
	v_ashrrev_i32_e32 v41, 31, v40
	v_ashrrev_i32_e32 v43, 31, v42
	v_add_u32_e32 v52, 16, v42
	v_lshl_add_u64 v[38:39], v[40:41], 1, s[46:47]
	v_lshlrev_b64 v[2:3], 11, v[42:43]
	v_ashrrev_i32_e32 v53, 31, v52
	v_add_u32_e32 v48, 32, v42
	v_lshl_add_u64 v[56:57], v[38:39], 0, v[2:3]
	v_lshlrev_b64 v[2:3], 11, v[52:53]
	v_ashrrev_i32_e32 v49, 31, v48
	v_add_u32_e32 v44, 48, v42
	v_lshl_add_u64 v[54:55], v[38:39], 0, v[2:3]
	v_lshlrev_b64 v[2:3], 11, v[48:49]
	v_ashrrev_i32_e32 v45, 31, v44
	v_lshl_add_u64 v[50:51], v[38:39], 0, v[2:3]
	v_lshlrev_b64 v[2:3], 11, v[44:45]
	global_load_dwordx4 v[30:33], v[56:57], off
	global_load_dwordx4 v[26:29], v[56:57], off offset:256
	v_lshl_add_u64 v[46:47], v[38:39], 0, v[2:3]
	global_load_dwordx4 v[22:25], v[54:55], off
	global_load_dwordx4 v[18:21], v[54:55], off offset:256
	global_load_dwordx4 v[14:17], v[50:51], off
	global_load_dwordx4 v[10:13], v[50:51], off offset:256
	global_load_dwordx4 v[6:9], v[46:47], off
	global_load_dwordx4 v[2:5], v[46:47], off offset:256
	s_mov_b64 s[8:9], 0x40000
	v_lshl_add_u64 v[62:63], v[56:57], 0, s[8:9]
	global_load_dwordx4 v[194:197], v[62:63], off
	global_load_dwordx4 v[198:201], v[62:63], off offset:256
	v_lshl_add_u64 v[62:63], v[54:55], 0, s[8:9]
	global_load_dwordx4 v[202:205], v[62:63], off
	global_load_dwordx4 v[206:209], v[62:63], off offset:256
	v_lshl_add_u64 v[62:63], v[50:51], 0, s[8:9]
	global_load_dwordx4 v[210:213], v[62:63], off
	global_load_dwordx4 v[224:227], v[62:63], off offset:256
	v_lshl_add_u64 v[62:63], v[46:47], 0, s[8:9]
	global_load_dwordx4 v[228:231], v[62:63], off
	v_cndmask_b32_e64 v34, 0, 1, s[74:75]
	v_lshlrev_b64 v[60:61], 10, v[42:43]
	v_cmp_ne_u32_e64 s[6:7], 1, v34
	v_lshl_add_u64 v[58:59], v[60:61], 0, v[40:41]
	s_mov_b64 s[8:9], -1
	s_andn2_b64 vcc, exec, s[74:75]
	v_lshl_add_u64 v[58:59], v[58:59], 2, s[54:55]
	s_waitcnt vmcnt(0)
	v_lshlrev_b32_e32 v34, 16, v30
	v_and_b32_e32 v35, 0xffff0000, v30
	v_lshlrev_b32_e32 v30, 16, v31
	v_and_b32_e32 v31, 0xffff0000, v31
	v_lshlrev_b32_e32 v62, 16, v32
	v_and_b32_e32 v63, 0xffff0000, v32
	v_lshlrev_b32_e32 v32, 16, v33
	v_and_b32_e32 v33, 0xffff0000, v33
	v_pk_fma_f32 v[36:37], s[72:73], v[192:193], v[30:31]
	v_pk_fma_f32 v[34:35], s[52:53], v[190:191], v[34:35]
	v_pk_fma_f32 v[32:33], s[72:73], v[188:189], v[32:33]
	v_pk_fma_f32 v[30:31], s[52:53], v[186:187], v[62:63]
	s_cbranch_vccnz .LBB0_380
	s_mov_b64 s[8:9], 0
	global_store_dwordx4 v[58:59], v[34:37], off
	global_store_dwordx4 v[58:59], v[30:33], off offset:16

;     __device__ __forceinline__ void operator()(AccRef acc, const pg8::Unit& u, int wr, int wc, int fr, int fq) const {
;     ...
;         for (int ai = 0; ai < 2; ++ai) {
;             v4u xw[4][2];
; #pragma unroll
;             for (int m = 0; m < 4; ++m)
; #pragma unroll
;                 for (int bj = 0; bj < 2; ++bj) xw[m][bj] = *(const v4u*)(xb + (size_t)(row0 + ai * 128 + m * 16) * D + col0 + bj * 128);
; #pragma unroll
;             for (int m = 0; m < 4; ++m) {
;                 const int row = row0 + ai * 128 + m * 16;
;                 float ss = 0.f;
; #pragma unroll
;                 for (int bj = 0; bj < 2; ++bj) {
;                     const size_t p = (size_t)row * D + col0 + bj * 128;
;                     const v4u w0 = xw[m][bj];
;                     f32x4 a = {bflo(w0.x), bfhi(w0.x), bflo(w0.y), bfhi(w0.y)}, b = {bflo(w0.z), bfhi(w0.z), bflo(w0.w), bfhi(w0.w)};
;                     a = a + acc[ai][bj][m][0] * scale; b = b + acc[ai][bj][m][1] * scale;
;                     if (outf) { *(f32x4*)(outf + p) = a; *(f32x4*)(outf + p + 4) = b; }
.LBB0_426:
	v_add_u32_e32 v54, 0x80, v42
	v_ashrrev_i32_e32 v55, 31, v54
	v_add_u32_e32 v50, 0x90, v42
	s_waitcnt lgkmcnt(0)
	v_lshlrev_b64 v[2:3], 11, v[54:55]
	v_ashrrev_i32_e32 v51, 31, v50
	v_add_u32_e32 v46, 0xa0, v42
	v_lshl_add_u64 v[56:57], v[38:39], 0, v[2:3]
	v_lshlrev_b64 v[2:3], 11, v[50:51]
	v_ashrrev_i32_e32 v47, 31, v46
	v_add_u32_e32 v42, 0xb0, v42
	v_lshl_add_u64 v[52:53], v[38:39], 0, v[2:3]
	v_lshlrev_b64 v[2:3], 11, v[46:47]
	v_ashrrev_i32_e32 v43, 31, v42
	v_lshl_add_u64 v[48:49], v[38:39], 0, v[2:3]
	v_lshlrev_b64 v[2:3], 11, v[42:43]
	v_mov_b64_e32 v[30:31], v[194:195]
	v_mov_b64_e32 v[32:33], v[196:197]
	v_mov_b64_e32 v[26:27], v[198:199]
	v_mov_b64_e32 v[28:29], v[200:201]
	v_lshl_add_u64 v[44:45], v[38:39], 0, v[2:3]
	v_mov_b64_e32 v[22:23], v[202:203]
	v_mov_b64_e32 v[24:25], v[204:205]
	v_mov_b64_e32 v[18:19], v[206:207]
	v_mov_b64_e32 v[20:21], v[208:209]
	v_mov_b64_e32 v[14:15], v[210:211]
	v_mov_b64_e32 v[16:17], v[212:213]
	v_mov_b64_e32 v[10:11], v[224:225]
	v_mov_b64_e32 v[12:13], v[226:227]
	v_mov_b64_e32 v[6:7], v[228:229]
	v_mov_b64_e32 v[8:9], v[230:231]
	global_load_dwordx4 v[2:5], v[44:45], off offset:256
	v_lshlrev_b64 v[60:61], 10, v[54:55]
	v_lshl_add_u64 v[58:59], v[60:61], 0, v[40:41]
	s_mov_b64 s[12:13], -1
	s_and_b64 vcc, exec, s[6:7]
	v_lshl_add_u64 v[58:59], v[58:59], 2, s[54:55]
	s_nop 1
	v_lshlrev_b32_e32 v34, 16, v30
	v_and_b32_e32 v35, 0xffff0000, v30
	v_lshlrev_b32_e32 v30, 16, v31
	v_and_b32_e32 v31, 0xffff0000, v31
	v_lshlrev_b32_e32 v62, 16, v32
	v_and_b32_e32 v63, 0xffff0000, v32
	v_lshlrev_b32_e32 v32, 16, v33
	v_and_b32_e32 v33, 0xffff0000, v33
	v_pk_fma_f32 v[36:37], s[72:73], v[128:129], v[30:31]
	v_pk_fma_f32 v[34:35], s[52:53], v[126:127], v[34:35]
	v_pk_fma_f32 v[32:33], s[72:73], v[124:125], v[32:33]
	v_pk_fma_f32 v[30:31], s[52:53], v[122:123], v[62:63]
	s_cbranch_vccnz .LBB0_428
	s_mov_b64 s[12:13], 0
	global_store_dwordx4 v[58:59], v[34:37], off
	global_store_dwordx4 v[58:59], v[30:33], off offset:16

; __device__ __forceinline__ unsigned pk2(float lo, float hi) { f32x2_t v = {lo, hi}; bf16x2_t b = __builtin_convertvector(v, bf16x2_t); return __builtin_bit_cast(unsigned, b); }
;     __device__ __forceinline__ void operator()(AccRef acc, const pg8::Unit& u, int wr, int wc, int fr, int fq) const {
;     ...
;                 for (int bj = 0; bj < 2; ++bj) {
;                     const size_t p = (size_t)row * D + col0 + bj * 128;
;                     const v4u w0 = xw[m][bj];
;                     f32x4 a = {bflo(w0.x), bfhi(w0.x), bflo(w0.y), bfhi(w0.y)}, b = {bflo(w0.z), bfhi(w0.z), bflo(w0.w), bfhi(w0.w)};
;                     a = a + acc[ai][bj][m][0] * scale; b = b + acc[ai][bj][m][1] * scale;
;                     if (outf) { *(f32x4*)(outf + p) = a; *(f32x4*)(outf + p + 4) = b; }
;                     else {
;                         ss += (a[0] * a[0] + a[1] * a[1]) + (a[2] * a[2] + a[3] * a[3]) + (b[0] * b[0] + b[1] * b[1]) + (b[2] * b[2] + b[3] * b[3]);
;                         v4u w; w.x = pk2(a[0], a[1]); w.y = pk2(a[2], a[3]); w.z = pk2(b[0], b[1]); w.w = pk2(b[2], b[3]);
;                         *(v4u*)(xb + p) = w;
.LBB0_430:
	s_nop 1
	v_lshlrev_b32_e32 v30, 16, v26
	v_and_b32_e32 v31, 0xffff0000, v26
	v_lshlrev_b32_e32 v26, 16, v27
	v_and_b32_e32 v27, 0xffff0000, v27
	v_lshlrev_b32_e32 v34, 16, v28
	v_and_b32_e32 v35, 0xffff0000, v28
	v_lshlrev_b32_e32 v32, 16, v29
	v_and_b32_e32 v33, 0xffff0000, v29
	v_pk_fma_f32 v[28:29], s[72:73], v[120:121], v[26:27]
	v_pk_fma_f32 v[26:27], s[52:53], v[118:119], v[30:31]
	v_pk_fma_f32 v[32:33], s[72:73], v[116:117], v[32:33]
	v_pk_fma_f32 v[30:31], s[52:53], v[114:115], v[34:35]
	s_and_b64 vcc, exec, s[6:7]
	s_mov_b64 s[12:13], -1
	s_cbranch_vccnz .LBB0_433
	global_store_dwordx4 v[58:59], v[26:29], off offset:512
	global_store_dwordx4 v[58:59], v[30:33], off offset:528
	s_cbranch_execz .LBB0_434

;     __device__ __forceinline__ void operator()(AccRef acc, const pg8::Unit& u, int wr, int wc, int fr, int fq) const {
;     ...
;             for (int m = 0; m < 4; ++m) {
;                 const int row = row0 + ai * 128 + m * 16;
;                 float ss = 0.f;
; #pragma unroll
;                 for (int bj = 0; bj < 2; ++bj) {
;                     const size_t p = (size_t)row * D + col0 + bj * 128;
;                     const v4u w0 = xw[m][bj];
;                     f32x4 a = {bflo(w0.x), bfhi(w0.x), bflo(w0.y), bfhi(w0.y)}, b = {bflo(w0.z), bfhi(w0.z), bflo(w0.w), bfhi(w0.w)};
;                     a = a + acc[ai][bj][m][0] * scale; b = b + acc[ai][bj][m][1] * scale;
;                     if (outf) { *(f32x4*)(outf + p) = a; *(f32x4*)(outf + p + 4) = b; }
.LBB0_438:
	v_lshlrev_b64 v[32:33], 10, v[50:51]
	v_lshl_add_u64 v[30:31], v[32:33], 0, v[40:41]
	s_nop 1
	v_lshlrev_b32_e32 v26, 16, v22
	s_waitcnt lgkmcnt(0)
	v_and_b32_e32 v27, 0xffff0000, v22
	v_lshlrev_b32_e32 v22, 16, v23
	v_and_b32_e32 v23, 0xffff0000, v23
	v_lshlrev_b32_e32 v34, 16, v24
	v_and_b32_e32 v35, 0xffff0000, v24
	v_lshlrev_b32_e32 v28, 16, v25
	v_and_b32_e32 v29, 0xffff0000, v25
	v_pk_fma_f32 v[24:25], s[72:73], v[112:113], v[22:23]
	v_pk_fma_f32 v[22:23], s[52:53], v[110:111], v[26:27]
	v_pk_fma_f32 v[28:29], s[72:73], v[108:109], v[28:29]
	v_pk_fma_f32 v[26:27], s[52:53], v[106:107], v[34:35]
	s_mov_b64 s[12:13], -1
	s_and_b64 vcc, exec, s[6:7]
	v_lshl_add_u64 v[30:31], v[30:31], 2, s[54:55]
	s_cbranch_vccnz .LBB0_440
	s_mov_b64 s[12:13], 0
	global_store_dwordx4 v[30:31], v[22:25], off
	global_store_dwordx4 v[30:31], v[26:29], off offset:16

;     __device__ __forceinline__ void operator()(AccRef acc, const pg8::Unit& u, int wr, int wc, int fr, int fq) const {
;     ...
;             for (int m = 0; m < 4; ++m) {
;                 const int row = row0 + ai * 128 + m * 16;
;                 float ss = 0.f;
; #pragma unroll
;                 for (int bj = 0; bj < 2; ++bj) {
;                     const size_t p = (size_t)row * D + col0 + bj * 128;
;                     const v4u w0 = xw[m][bj];
;                     f32x4 a = {bflo(w0.x), bfhi(w0.x), bflo(w0.y), bfhi(w0.y)}, b = {bflo(w0.z), bfhi(w0.z), bflo(w0.w), bfhi(w0.w)};
;                     a = a + acc[ai][bj][m][0] * scale; b = b + acc[ai][bj][m][1] * scale;
;                     if (outf) { *(f32x4*)(outf + p) = a; *(f32x4*)(outf + p + 4) = b; }
.LBB0_442:
	s_nop 1
	s_nop 0
	v_lshlrev_b32_e32 v22, 16, v18
	v_and_b32_e32 v23, 0xffff0000, v18
	v_lshlrev_b32_e32 v18, 16, v19
	v_and_b32_e32 v19, 0xffff0000, v19
	v_lshlrev_b32_e32 v26, 16, v20
	v_and_b32_e32 v27, 0xffff0000, v20
	v_lshlrev_b32_e32 v24, 16, v21
	v_and_b32_e32 v25, 0xffff0000, v21
	v_pk_fma_f32 v[20:21], s[72:73], v[104:105], v[18:19]
	v_pk_fma_f32 v[18:19], s[52:53], v[102:103], v[22:23]
	v_pk_fma_f32 v[24:25], s[72:73], v[100:101], v[24:25]
	v_pk_fma_f32 v[22:23], s[52:53], v[98:99], v[26:27]
	s_and_b64 vcc, exec, s[6:7]
	s_mov_b64 s[12:13], -1
	s_cbranch_vccnz .LBB0_445
	global_store_dwordx4 v[30:31], v[18:21], off offset:512
	global_store_dwordx4 v[30:31], v[22:25], off offset:528
	s_cbranch_execz .LBB0_446

;     __device__ __forceinline__ void operator()(AccRef acc, const pg8::Unit& u, int wr, int wc, int fr, int fq) const {
;     ...
;             for (int m = 0; m < 4; ++m) {
;                 const int row = row0 + ai * 128 + m * 16;
;                 float ss = 0.f;
; #pragma unroll
;                 for (int bj = 0; bj < 2; ++bj) {
;                     const size_t p = (size_t)row * D + col0 + bj * 128;
;                     const v4u w0 = xw[m][bj];
;                     f32x4 a = {bflo(w0.x), bfhi(w0.x), bflo(w0.y), bfhi(w0.y)}, b = {bflo(w0.z), bfhi(w0.z), bflo(w0.w), bfhi(w0.w)};
;                     a = a + acc[ai][bj][m][0] * scale; b = b + acc[ai][bj][m][1] * scale;
;                     if (outf) { *(f32x4*)(outf + p) = a; *(f32x4*)(outf + p + 4) = b; }
.LBB0_450:
	v_lshlrev_b64 v[24:25], 10, v[46:47]
	v_lshl_add_u64 v[22:23], v[24:25], 0, v[40:41]
	s_nop 1
	v_lshlrev_b32_e32 v18, 16, v14
	s_waitcnt lgkmcnt(0)
	v_and_b32_e32 v19, 0xffff0000, v14
	v_lshlrev_b32_e32 v14, 16, v15
	v_and_b32_e32 v15, 0xffff0000, v15
	v_lshlrev_b32_e32 v26, 16, v16
	v_and_b32_e32 v27, 0xffff0000, v16
	v_lshlrev_b32_e32 v20, 16, v17
	v_and_b32_e32 v21, 0xffff0000, v17
	v_pk_fma_f32 v[16:17], s[72:73], v[96:97], v[14:15]
	v_pk_fma_f32 v[14:15], s[52:53], v[94:95], v[18:19]
	v_pk_fma_f32 v[20:21], s[72:73], v[92:93], v[20:21]
	v_pk_fma_f32 v[18:19], s[52:53], v[90:91], v[26:27]
	s_mov_b64 s[12:13], -1
	s_and_b64 vcc, exec, s[6:7]
	v_lshl_add_u64 v[22:23], v[22:23], 2, s[54:55]
	s_cbranch_vccnz .LBB0_452
	s_mov_b64 s[12:13], 0
	global_store_dwordx4 v[22:23], v[14:17], off
	global_store_dwordx4 v[22:23], v[18:21], off offset:16

;     __device__ __forceinline__ void operator()(AccRef acc, const pg8::Unit& u, int wr, int wc, int fr, int fq) const {
;     ...
;             for (int m = 0; m < 4; ++m) {
;                 const int row = row0 + ai * 128 + m * 16;
;                 float ss = 0.f;
; #pragma unroll
;                 for (int bj = 0; bj < 2; ++bj) {
;                     const size_t p = (size_t)row * D + col0 + bj * 128;
;                     const v4u w0 = xw[m][bj];
;                     f32x4 a = {bflo(w0.x), bfhi(w0.x), bflo(w0.y), bfhi(w0.y)}, b = {bflo(w0.z), bfhi(w0.z), bflo(w0.w), bfhi(w0.w)};
;                     a = a + acc[ai][bj][m][0] * scale; b = b + acc[ai][bj][m][1] * scale;
;                     if (outf) { *(f32x4*)(outf + p) = a; *(f32x4*)(outf + p + 4) = b; }
.LBB0_454:
	s_nop 1
	s_nop 0
	v_lshlrev_b32_e32 v14, 16, v10
	v_and_b32_e32 v15, 0xffff0000, v10
	v_lshlrev_b32_e32 v10, 16, v11
	v_and_b32_e32 v11, 0xffff0000, v11
	v_lshlrev_b32_e32 v18, 16, v12
	v_and_b32_e32 v19, 0xffff0000, v12
	v_lshlrev_b32_e32 v16, 16, v13
	v_and_b32_e32 v17, 0xffff0000, v13
	v_pk_fma_f32 v[12:13], s[72:73], v[88:89], v[10:11]
	v_pk_fma_f32 v[10:11], s[52:53], v[86:87], v[14:15]
	v_pk_fma_f32 v[16:17], s[72:73], v[84:85], v[16:17]
	v_pk_fma_f32 v[14:15], s[52:53], v[82:83], v[18:19]
	s_and_b64 vcc, exec, s[6:7]
	s_mov_b64 s[12:13], -1
	s_cbranch_vccnz .LBB0_457
	global_store_dwordx4 v[22:23], v[10:13], off offset:512
	global_store_dwordx4 v[22:23], v[14:17], off offset:528
	s_cbranch_execz .LBB0_458

;     __device__ __forceinline__ void operator()(AccRef acc, const pg8::Unit& u, int wr, int wc, int fr, int fq) const {
;     ...
;             for (int m = 0; m < 4; ++m) {
;                 const int row = row0 + ai * 128 + m * 16;
;                 float ss = 0.f;
; #pragma unroll
;                 for (int bj = 0; bj < 2; ++bj) {
;                     const size_t p = (size_t)row * D + col0 + bj * 128;
;                     const v4u w0 = xw[m][bj];
;                     f32x4 a = {bflo(w0.x), bfhi(w0.x), bflo(w0.y), bfhi(w0.y)}, b = {bflo(w0.z), bfhi(w0.z), bflo(w0.w), bfhi(w0.w)};
;                     a = a + acc[ai][bj][m][0] * scale; b = b + acc[ai][bj][m][1] * scale;
;                     if (outf) { *(f32x4*)(outf + p) = a; *(f32x4*)(outf + p + 4) = b; }
.LBB0_462:
	v_lshlrev_b64 v[16:17], 10, v[42:43]
	v_lshl_add_u64 v[14:15], v[16:17], 0, v[40:41]
	s_nop 1
	v_lshlrev_b32_e32 v10, 16, v6
	s_waitcnt lgkmcnt(0)
	v_and_b32_e32 v11, 0xffff0000, v6
	v_lshlrev_b32_e32 v6, 16, v7
	v_and_b32_e32 v7, 0xffff0000, v7
	v_lshlrev_b32_e32 v18, 16, v8
	v_and_b32_e32 v19, 0xffff0000, v8
	v_lshlrev_b32_e32 v12, 16, v9
	v_and_b32_e32 v13, 0xffff0000, v9
	v_pk_fma_f32 v[8:9], s[72:73], v[80:81], v[6:7]
	v_pk_fma_f32 v[6:7], s[52:53], v[78:79], v[10:11]
	v_pk_fma_f32 v[12:13], s[72:73], v[76:77], v[12:13]
	v_pk_fma_f32 v[10:11], s[52:53], v[74:75], v[18:19]
	s_mov_b64 s[12:13], -1
	s_and_b64 vcc, exec, s[6:7]
	v_lshl_add_u64 v[14:15], v[14:15], 2, s[54:55]
	s_cbranch_vccnz .LBB0_464
	s_mov_b64 s[12:13], 0
	global_store_dwordx4 v[14:15], v[6:9], off
	global_store_dwordx4 v[14:15], v[10:13], off offset:16
